# SwiGLU tile epilogue regenerated: packed mul/fma formulation with rstd folded (fewer VALU cycles per output), same f32 exp2+rcp and bf16 pack
# speedup vs baseline: 1.0230x; 1.0095x over previous
.Lg131_nox:
	v_lshl_add_u32 v180, s51, 10, v147
	ds_read2_b32 v[152:153], v180 offset1:16
	ds_read2_b32 v[154:155], v180 offset0:32 offset1:48
	ds_read2_b32 v[156:157], v180 offset0:128 offset1:144
	ds_read2_b32 v[158:159], v180 offset0:160 offset1:176
	v_lshl_or_b32 v181, s52, 7, v148
	v_lshl_add_u32 v182, s18, 8, v144
	s_and_b64 vcc, exec, s[4:5]
	s_mov_b32 s52, s10
	s_mov_b32 s18, s12
	s_mov_b64 s[26:27], s[16:17]
	s_mov_b32 s51, s50
	s_mov_b64 s[20:21], s[14:15]
	v_mul_u32_u24_e32 v183, s49, v182
	v_lshl_add_u32 v183, v181, 1, v183
	s_waitcnt lgkmcnt(0)
	v_mul_f32_e32 v176, 0xbfb8aa3b, v152
	v_mul_f32_e32 v177, v152, v152
	v_rcp_f32_e32 v178, v177
	v_pk_mul_f32 v[160:161], v[124:125], v[176:177] op_sel_hi:[1,0]
	v_pk_mul_f32 v[162:163], v[126:127], v[176:177] op_sel_hi:[1,0]
	v_pk_mul_f32 v[164:165], v[120:121], v[176:177] op_sel_hi:[1,0]
	v_pk_mul_f32 v[166:167], v[122:123], v[176:177] op_sel_hi:[1,0]
	v_exp_f32_e32 v160, v160
	v_exp_f32_e32 v161, v161
	v_exp_f32_e32 v162, v162
	v_exp_f32_e32 v163, v163
	v_exp_f32_e32 v164, v164
	v_exp_f32_e32 v165, v165
	v_exp_f32_e32 v166, v166
	v_exp_f32_e32 v167, v167
	v_pk_fma_f32 v[160:161], v[160:161], v[178:179], v[178:179] op_sel_hi:[1,0,0]
	v_pk_fma_f32 v[162:163], v[162:163], v[178:179], v[178:179] op_sel_hi:[1,0,0]
	v_pk_fma_f32 v[164:165], v[164:165], v[178:179], v[178:179] op_sel_hi:[1,0,0]
	v_pk_fma_f32 v[166:167], v[166:167], v[178:179], v[178:179] op_sel_hi:[1,0,0]
	v_rcp_f32_e32 v160, v160
	v_rcp_f32_e32 v161, v161
	v_rcp_f32_e32 v162, v162
	v_rcp_f32_e32 v163, v163
	v_rcp_f32_e32 v164, v164
	v_rcp_f32_e32 v165, v165
	v_rcp_f32_e32 v166, v166
	v_rcp_f32_e32 v167, v167
	v_pk_mul_f32 v[124:125], v[124:125], v[116:117]
	v_pk_mul_f32 v[126:127], v[126:127], v[118:119]
	v_pk_mul_f32 v[120:121], v[120:121], v[112:113]
	v_pk_mul_f32 v[122:123], v[122:123], v[114:115]
	v_pk_mul_f32 v[124:125], v[124:125], v[160:161]
	v_pk_mul_f32 v[126:127], v[126:127], v[162:163]
	v_pk_mul_f32 v[120:121], v[120:121], v[164:165]
	v_pk_mul_f32 v[122:123], v[122:123], v[166:167]
	v_cvt_pk_bf16_f32 v168, v124, v125
	v_cvt_pk_bf16_f32 v169, v126, v127
	v_cvt_pk_bf16_f32 v170, v120, v121
	v_cvt_pk_bf16_f32 v171, v122, v123
	global_store_dwordx4 v183, v[168:171], s[6:7]
	v_mul_f32_e32 v176, 0xbfb8aa3b, v153
	v_mul_f32_e32 v177, v153, v153
	v_rcp_f32_e32 v178, v177
	v_pk_mul_f32 v[160:161], v[108:109], v[176:177] op_sel_hi:[1,0]
	v_pk_mul_f32 v[162:163], v[110:111], v[176:177] op_sel_hi:[1,0]
	v_pk_mul_f32 v[164:165], v[104:105], v[176:177] op_sel_hi:[1,0]
	v_pk_mul_f32 v[166:167], v[106:107], v[176:177] op_sel_hi:[1,0]
	v_exp_f32_e32 v160, v160
	v_exp_f32_e32 v161, v161
	v_exp_f32_e32 v162, v162
	v_exp_f32_e32 v163, v163
	v_exp_f32_e32 v164, v164
	v_exp_f32_e32 v165, v165
	v_exp_f32_e32 v166, v166
	v_exp_f32_e32 v167, v167
	v_pk_fma_f32 v[160:161], v[160:161], v[178:179], v[178:179] op_sel_hi:[1,0,0]
	v_pk_fma_f32 v[162:163], v[162:163], v[178:179], v[178:179] op_sel_hi:[1,0,0]
	v_pk_fma_f32 v[164:165], v[164:165], v[178:179], v[178:179] op_sel_hi:[1,0,0]
	v_pk_fma_f32 v[166:167], v[166:167], v[178:179], v[178:179] op_sel_hi:[1,0,0]
	v_rcp_f32_e32 v160, v160
	v_rcp_f32_e32 v161, v161
	v_rcp_f32_e32 v162, v162
	v_rcp_f32_e32 v163, v163
	v_rcp_f32_e32 v164, v164
	v_rcp_f32_e32 v165, v165
	v_rcp_f32_e32 v166, v166
	v_rcp_f32_e32 v167, v167
	v_pk_mul_f32 v[108:109], v[108:109], v[100:101]
	v_pk_mul_f32 v[110:111], v[110:111], v[102:103]
	v_pk_mul_f32 v[104:105], v[104:105], v[96:97]
	v_pk_mul_f32 v[106:107], v[106:107], v[98:99]
	v_pk_mul_f32 v[108:109], v[108:109], v[160:161]
	v_pk_mul_f32 v[110:111], v[110:111], v[162:163]
	v_pk_mul_f32 v[104:105], v[104:105], v[164:165]
	v_pk_mul_f32 v[106:107], v[106:107], v[166:167]
	v_cvt_pk_bf16_f32 v172, v108, v109
	v_cvt_pk_bf16_f32 v173, v110, v111
	v_cvt_pk_bf16_f32 v174, v104, v105
	v_cvt_pk_bf16_f32 v175, v106, v107
	v_add_u32_e32 v185, 0x16000, v183
	global_store_dwordx4 v185, v[172:175], s[6:7]
	v_mul_f32_e32 v176, 0xbfb8aa3b, v154
	v_mul_f32_e32 v177, v154, v154
	v_rcp_f32_e32 v178, v177
	v_pk_mul_f32 v[160:161], v[92:93], v[176:177] op_sel_hi:[1,0]
	v_pk_mul_f32 v[162:163], v[94:95], v[176:177] op_sel_hi:[1,0]
	v_pk_mul_f32 v[164:165], v[88:89], v[176:177] op_sel_hi:[1,0]
	v_pk_mul_f32 v[166:167], v[90:91], v[176:177] op_sel_hi:[1,0]
	v_exp_f32_e32 v160, v160
	v_exp_f32_e32 v161, v161
	v_exp_f32_e32 v162, v162
	v_exp_f32_e32 v163, v163
	v_exp_f32_e32 v164, v164
	v_exp_f32_e32 v165, v165
	v_exp_f32_e32 v166, v166
	v_exp_f32_e32 v167, v167
	v_pk_fma_f32 v[160:161], v[160:161], v[178:179], v[178:179] op_sel_hi:[1,0,0]
	v_pk_fma_f32 v[162:163], v[162:163], v[178:179], v[178:179] op_sel_hi:[1,0,0]
	v_pk_fma_f32 v[164:165], v[164:165], v[178:179], v[178:179] op_sel_hi:[1,0,0]
	v_pk_fma_f32 v[166:167], v[166:167], v[178:179], v[178:179] op_sel_hi:[1,0,0]
	v_rcp_f32_e32 v160, v160
	v_rcp_f32_e32 v161, v161
	v_rcp_f32_e32 v162, v162
	v_rcp_f32_e32 v163, v163
	v_rcp_f32_e32 v164, v164
	v_rcp_f32_e32 v165, v165
	v_rcp_f32_e32 v166, v166
	v_rcp_f32_e32 v167, v167
	v_pk_mul_f32 v[92:93], v[92:93], v[84:85]
	v_pk_mul_f32 v[94:95], v[94:95], v[86:87]
	v_pk_mul_f32 v[88:89], v[88:89], v[80:81]
	v_pk_mul_f32 v[90:91], v[90:91], v[82:83]
	v_pk_mul_f32 v[92:93], v[92:93], v[160:161]
	v_pk_mul_f32 v[94:95], v[94:95], v[162:163]
	v_pk_mul_f32 v[88:89], v[88:89], v[164:165]
	v_pk_mul_f32 v[90:91], v[90:91], v[166:167]
	v_cvt_pk_bf16_f32 v168, v92, v93
	v_cvt_pk_bf16_f32 v169, v94, v95
	v_cvt_pk_bf16_f32 v170, v88, v89
	v_cvt_pk_bf16_f32 v171, v90, v91
	v_add_u32_e32 v184, 0x2c000, v183
	global_store_dwordx4 v184, v[168:171], s[6:7]
	v_mul_f32_e32 v176, 0xbfb8aa3b, v155
	v_mul_f32_e32 v177, v155, v155
	v_rcp_f32_e32 v178, v177
	v_pk_mul_f32 v[160:161], v[76:77], v[176:177] op_sel_hi:[1,0]
	v_pk_mul_f32 v[162:163], v[78:79], v[176:177] op_sel_hi:[1,0]
	v_pk_mul_f32 v[164:165], v[72:73], v[176:177] op_sel_hi:[1,0]
	v_pk_mul_f32 v[166:167], v[74:75], v[176:177] op_sel_hi:[1,0]
	v_exp_f32_e32 v160, v160
	v_exp_f32_e32 v161, v161
	v_exp_f32_e32 v162, v162
	v_exp_f32_e32 v163, v163
	v_exp_f32_e32 v164, v164
	v_exp_f32_e32 v165, v165
	v_exp_f32_e32 v166, v166
	v_exp_f32_e32 v167, v167
	v_pk_fma_f32 v[160:161], v[160:161], v[178:179], v[178:179] op_sel_hi:[1,0,0]
	v_pk_fma_f32 v[162:163], v[162:163], v[178:179], v[178:179] op_sel_hi:[1,0,0]
	v_pk_fma_f32 v[164:165], v[164:165], v[178:179], v[178:179] op_sel_hi:[1,0,0]
	v_pk_fma_f32 v[166:167], v[166:167], v[178:179], v[178:179] op_sel_hi:[1,0,0]
	v_rcp_f32_e32 v160, v160
	v_rcp_f32_e32 v161, v161
	v_rcp_f32_e32 v162, v162
	v_rcp_f32_e32 v163, v163
	v_rcp_f32_e32 v164, v164
	v_rcp_f32_e32 v165, v165
	v_rcp_f32_e32 v166, v166
	v_rcp_f32_e32 v167, v167
	v_pk_mul_f32 v[76:77], v[76:77], v[68:69]
	v_pk_mul_f32 v[78:79], v[78:79], v[70:71]
	v_pk_mul_f32 v[72:73], v[72:73], v[64:65]
	v_pk_mul_f32 v[74:75], v[74:75], v[66:67]
	v_pk_mul_f32 v[76:77], v[76:77], v[160:161]
	v_pk_mul_f32 v[78:79], v[78:79], v[162:163]
	v_pk_mul_f32 v[72:73], v[72:73], v[164:165]
	v_pk_mul_f32 v[74:75], v[74:75], v[166:167]
	v_cvt_pk_bf16_f32 v172, v76, v77
	v_cvt_pk_bf16_f32 v173, v78, v79
	v_cvt_pk_bf16_f32 v174, v72, v73
	v_cvt_pk_bf16_f32 v175, v74, v75
	v_add_u32_e32 v185, 0x42000, v183
	global_store_dwordx4 v185, v[172:175], s[6:7]
	v_mul_f32_e32 v176, 0xbfb8aa3b, v156
	v_mul_f32_e32 v177, v156, v156
	v_rcp_f32_e32 v178, v177
	v_pk_mul_f32 v[160:161], v[60:61], v[176:177] op_sel_hi:[1,0]
	v_pk_mul_f32 v[162:163], v[62:63], v[176:177] op_sel_hi:[1,0]
	v_pk_mul_f32 v[164:165], v[56:57], v[176:177] op_sel_hi:[1,0]
	v_pk_mul_f32 v[166:167], v[58:59], v[176:177] op_sel_hi:[1,0]
	v_exp_f32_e32 v160, v160
	v_exp_f32_e32 v161, v161
	v_exp_f32_e32 v162, v162
	v_exp_f32_e32 v163, v163
	v_exp_f32_e32 v164, v164
	v_exp_f32_e32 v165, v165
	v_exp_f32_e32 v166, v166
	v_exp_f32_e32 v167, v167
	v_pk_fma_f32 v[160:161], v[160:161], v[178:179], v[178:179] op_sel_hi:[1,0,0]
	v_pk_fma_f32 v[162:163], v[162:163], v[178:179], v[178:179] op_sel_hi:[1,0,0]
	v_pk_fma_f32 v[164:165], v[164:165], v[178:179], v[178:179] op_sel_hi:[1,0,0]
	v_pk_fma_f32 v[166:167], v[166:167], v[178:179], v[178:179] op_sel_hi:[1,0,0]
	v_rcp_f32_e32 v160, v160
	v_rcp_f32_e32 v161, v161
	v_rcp_f32_e32 v162, v162
	v_rcp_f32_e32 v163, v163
	v_rcp_f32_e32 v164, v164
	v_rcp_f32_e32 v165, v165
	v_rcp_f32_e32 v166, v166
	v_rcp_f32_e32 v167, v167
	v_pk_mul_f32 v[60:61], v[60:61], v[52:53]
	v_pk_mul_f32 v[62:63], v[62:63], v[54:55]
	v_pk_mul_f32 v[56:57], v[56:57], v[48:49]
	v_pk_mul_f32 v[58:59], v[58:59], v[50:51]
	v_pk_mul_f32 v[60:61], v[60:61], v[160:161]
	v_pk_mul_f32 v[62:63], v[62:63], v[162:163]
	v_pk_mul_f32 v[56:57], v[56:57], v[164:165]
	v_pk_mul_f32 v[58:59], v[58:59], v[166:167]
	v_cvt_pk_bf16_f32 v168, v60, v61
	v_cvt_pk_bf16_f32 v169, v62, v63
	v_cvt_pk_bf16_f32 v170, v56, v57
	v_cvt_pk_bf16_f32 v171, v58, v59
	v_add_u32_e32 v184, 0xb0000, v183
	global_store_dwordx4 v184, v[168:171], s[6:7]
	v_mul_f32_e32 v176, 0xbfb8aa3b, v157
	v_mul_f32_e32 v177, v157, v157
	v_rcp_f32_e32 v178, v177
	v_pk_mul_f32 v[160:161], v[44:45], v[176:177] op_sel_hi:[1,0]
	v_pk_mul_f32 v[162:163], v[46:47], v[176:177] op_sel_hi:[1,0]
	v_pk_mul_f32 v[164:165], v[40:41], v[176:177] op_sel_hi:[1,0]
	v_pk_mul_f32 v[166:167], v[42:43], v[176:177] op_sel_hi:[1,0]
	v_exp_f32_e32 v160, v160
	v_exp_f32_e32 v161, v161
	v_exp_f32_e32 v162, v162
	v_exp_f32_e32 v163, v163
	v_exp_f32_e32 v164, v164
	v_exp_f32_e32 v165, v165
	v_exp_f32_e32 v166, v166
	v_exp_f32_e32 v167, v167
	v_pk_fma_f32 v[160:161], v[160:161], v[178:179], v[178:179] op_sel_hi:[1,0,0]
	v_pk_fma_f32 v[162:163], v[162:163], v[178:179], v[178:179] op_sel_hi:[1,0,0]
	v_pk_fma_f32 v[164:165], v[164:165], v[178:179], v[178:179] op_sel_hi:[1,0,0]
	v_pk_fma_f32 v[166:167], v[166:167], v[178:179], v[178:179] op_sel_hi:[1,0,0]
	v_rcp_f32_e32 v160, v160
	v_rcp_f32_e32 v161, v161
	v_rcp_f32_e32 v162, v162
	v_rcp_f32_e32 v163, v163
	v_rcp_f32_e32 v164, v164
	v_rcp_f32_e32 v165, v165
	v_rcp_f32_e32 v166, v166
	v_rcp_f32_e32 v167, v167
	v_pk_mul_f32 v[44:45], v[44:45], v[36:37]
	v_pk_mul_f32 v[46:47], v[46:47], v[38:39]
	v_pk_mul_f32 v[40:41], v[40:41], v[32:33]
	v_pk_mul_f32 v[42:43], v[42:43], v[34:35]
	v_pk_mul_f32 v[44:45], v[44:45], v[160:161]
	v_pk_mul_f32 v[46:47], v[46:47], v[162:163]
	v_pk_mul_f32 v[40:41], v[40:41], v[164:165]
	v_pk_mul_f32 v[42:43], v[42:43], v[166:167]
	v_cvt_pk_bf16_f32 v172, v44, v45
	v_cvt_pk_bf16_f32 v173, v46, v47
	v_cvt_pk_bf16_f32 v174, v40, v41
	v_cvt_pk_bf16_f32 v175, v42, v43
	v_add_u32_e32 v185, 0xc6000, v183
	global_store_dwordx4 v185, v[172:175], s[6:7]
	v_mul_f32_e32 v176, 0xbfb8aa3b, v158
	v_mul_f32_e32 v177, v158, v158
	v_rcp_f32_e32 v178, v177
	v_pk_mul_f32 v[160:161], v[28:29], v[176:177] op_sel_hi:[1,0]
	v_pk_mul_f32 v[162:163], v[30:31], v[176:177] op_sel_hi:[1,0]
	v_pk_mul_f32 v[164:165], v[24:25], v[176:177] op_sel_hi:[1,0]
	v_pk_mul_f32 v[166:167], v[26:27], v[176:177] op_sel_hi:[1,0]
	v_exp_f32_e32 v160, v160
	v_exp_f32_e32 v161, v161
	v_exp_f32_e32 v162, v162
	v_exp_f32_e32 v163, v163
	v_exp_f32_e32 v164, v164
	v_exp_f32_e32 v165, v165
	v_exp_f32_e32 v166, v166
	v_exp_f32_e32 v167, v167
	v_pk_fma_f32 v[160:161], v[160:161], v[178:179], v[178:179] op_sel_hi:[1,0,0]
	v_pk_fma_f32 v[162:163], v[162:163], v[178:179], v[178:179] op_sel_hi:[1,0,0]
	v_pk_fma_f32 v[164:165], v[164:165], v[178:179], v[178:179] op_sel_hi:[1,0,0]
	v_pk_fma_f32 v[166:167], v[166:167], v[178:179], v[178:179] op_sel_hi:[1,0,0]
	v_rcp_f32_e32 v160, v160
	v_rcp_f32_e32 v161, v161
	v_rcp_f32_e32 v162, v162
	v_rcp_f32_e32 v163, v163
	v_rcp_f32_e32 v164, v164
	v_rcp_f32_e32 v165, v165
	v_rcp_f32_e32 v166, v166
	v_rcp_f32_e32 v167, v167
	v_pk_mul_f32 v[28:29], v[28:29], v[20:21]
	v_pk_mul_f32 v[30:31], v[30:31], v[22:23]
	v_pk_mul_f32 v[24:25], v[24:25], v[16:17]
	v_pk_mul_f32 v[26:27], v[26:27], v[18:19]
	v_pk_mul_f32 v[28:29], v[28:29], v[160:161]
	v_pk_mul_f32 v[30:31], v[30:31], v[162:163]
	v_pk_mul_f32 v[24:25], v[24:25], v[164:165]
	v_pk_mul_f32 v[26:27], v[26:27], v[166:167]
	v_cvt_pk_bf16_f32 v168, v28, v29
	v_cvt_pk_bf16_f32 v169, v30, v31
	v_cvt_pk_bf16_f32 v170, v24, v25
	v_cvt_pk_bf16_f32 v171, v26, v27
	v_add_u32_e32 v184, 0xdc000, v183
	global_store_dwordx4 v184, v[168:171], s[6:7]
	v_mul_f32_e32 v176, 0xbfb8aa3b, v159
	v_mul_f32_e32 v177, v159, v159
	v_rcp_f32_e32 v178, v177
	v_pk_mul_f32 v[160:161], v[12:13], v[176:177] op_sel_hi:[1,0]
	v_pk_mul_f32 v[162:163], v[14:15], v[176:177] op_sel_hi:[1,0]
	v_pk_mul_f32 v[164:165], v[8:9], v[176:177] op_sel_hi:[1,0]
	v_pk_mul_f32 v[166:167], v[10:11], v[176:177] op_sel_hi:[1,0]
	v_exp_f32_e32 v160, v160
	v_exp_f32_e32 v161, v161
	v_exp_f32_e32 v162, v162
	v_exp_f32_e32 v163, v163
	v_exp_f32_e32 v164, v164
	v_exp_f32_e32 v165, v165
	v_exp_f32_e32 v166, v166
	v_exp_f32_e32 v167, v167
	v_pk_fma_f32 v[160:161], v[160:161], v[178:179], v[178:179] op_sel_hi:[1,0,0]
	v_pk_fma_f32 v[162:163], v[162:163], v[178:179], v[178:179] op_sel_hi:[1,0,0]
	v_pk_fma_f32 v[164:165], v[164:165], v[178:179], v[178:179] op_sel_hi:[1,0,0]
	v_pk_fma_f32 v[166:167], v[166:167], v[178:179], v[178:179] op_sel_hi:[1,0,0]
	v_rcp_f32_e32 v160, v160
	v_rcp_f32_e32 v161, v161
	v_rcp_f32_e32 v162, v162
	v_rcp_f32_e32 v163, v163
	v_rcp_f32_e32 v164, v164
	v_rcp_f32_e32 v165, v165
	v_rcp_f32_e32 v166, v166
	v_rcp_f32_e32 v167, v167
	v_pk_mul_f32 v[12:13], v[12:13], v[4:5]
	v_pk_mul_f32 v[14:15], v[14:15], v[6:7]
	v_pk_mul_f32 v[8:9], v[8:9], v[0:1]
	v_pk_mul_f32 v[10:11], v[10:11], v[2:3]
	v_pk_mul_f32 v[12:13], v[12:13], v[160:161]
	v_pk_mul_f32 v[14:15], v[14:15], v[162:163]
	v_pk_mul_f32 v[8:9], v[8:9], v[164:165]
	v_pk_mul_f32 v[10:11], v[10:11], v[166:167]
	v_cvt_pk_bf16_f32 v172, v12, v13
	v_cvt_pk_bf16_f32 v173, v14, v15
	v_cvt_pk_bf16_f32 v174, v8, v9
	v_cvt_pk_bf16_f32 v175, v10, v11
	v_add_u32_e32 v185, 0xf2000, v183
	global_store_dwordx4 v185, v[172:175], s[6:7]
	s_cbranch_vccz .LBB0_128
	s_waitcnt vmcnt(0)
	s_cmpk_gt_u32 s37, 0xff
	s_cbranch_scc1 .LBB0_135

.Lg893_nox:
	v_lshl_add_u32 v180, s51, 10, v146
	ds_read2_b32 v[152:153], v180 offset1:16
	ds_read2_b32 v[154:155], v180 offset0:32 offset1:48
	ds_read2_b32 v[156:157], v180 offset0:128 offset1:144
	ds_read2_b32 v[158:159], v180 offset0:160 offset1:176
	v_lshl_or_b32 v181, s52, 7, v147
	v_lshl_add_u32 v182, s18, 8, v144
	s_and_b64 vcc, exec, s[4:5]
	s_mov_b32 s52, s10
	s_mov_b32 s18, s12
	s_mov_b64 s[26:27], s[16:17]
	s_mov_b32 s51, s50
	s_mov_b64 s[20:21], s[14:15]
	v_mul_u32_u24_e32 v183, s49, v182
	v_lshl_add_u32 v183, v181, 1, v183
	s_waitcnt lgkmcnt(0)
	v_mul_f32_e32 v176, 0xbfb8aa3b, v152
	v_mul_f32_e32 v177, v152, v152
	v_rcp_f32_e32 v178, v177
	v_pk_mul_f32 v[160:161], v[124:125], v[176:177] op_sel_hi:[1,0]
	v_pk_mul_f32 v[162:163], v[126:127], v[176:177] op_sel_hi:[1,0]
	v_pk_mul_f32 v[164:165], v[120:121], v[176:177] op_sel_hi:[1,0]
	v_pk_mul_f32 v[166:167], v[122:123], v[176:177] op_sel_hi:[1,0]
	v_exp_f32_e32 v160, v160
	v_exp_f32_e32 v161, v161
	v_exp_f32_e32 v162, v162
	v_exp_f32_e32 v163, v163
	v_exp_f32_e32 v164, v164
	v_exp_f32_e32 v165, v165
	v_exp_f32_e32 v166, v166
	v_exp_f32_e32 v167, v167
	v_pk_fma_f32 v[160:161], v[160:161], v[178:179], v[178:179] op_sel_hi:[1,0,0]
	v_pk_fma_f32 v[162:163], v[162:163], v[178:179], v[178:179] op_sel_hi:[1,0,0]
	v_pk_fma_f32 v[164:165], v[164:165], v[178:179], v[178:179] op_sel_hi:[1,0,0]
	v_pk_fma_f32 v[166:167], v[166:167], v[178:179], v[178:179] op_sel_hi:[1,0,0]
	v_rcp_f32_e32 v160, v160
	v_rcp_f32_e32 v161, v161
	v_rcp_f32_e32 v162, v162
	v_rcp_f32_e32 v163, v163
	v_rcp_f32_e32 v164, v164
	v_rcp_f32_e32 v165, v165
	v_rcp_f32_e32 v166, v166
	v_rcp_f32_e32 v167, v167
	v_pk_mul_f32 v[124:125], v[124:125], v[116:117]
	v_pk_mul_f32 v[126:127], v[126:127], v[118:119]
	v_pk_mul_f32 v[120:121], v[120:121], v[112:113]
	v_pk_mul_f32 v[122:123], v[122:123], v[114:115]
	v_pk_mul_f32 v[124:125], v[124:125], v[160:161]
	v_pk_mul_f32 v[126:127], v[126:127], v[162:163]
	v_pk_mul_f32 v[120:121], v[120:121], v[164:165]
	v_pk_mul_f32 v[122:123], v[122:123], v[166:167]
	v_cvt_pk_bf16_f32 v168, v124, v125
	v_cvt_pk_bf16_f32 v169, v126, v127
	v_cvt_pk_bf16_f32 v170, v120, v121
	v_cvt_pk_bf16_f32 v171, v122, v123
	global_store_dwordx4 v183, v[168:171], s[6:7]
	v_mul_f32_e32 v176, 0xbfb8aa3b, v153
	v_mul_f32_e32 v177, v153, v153
	v_rcp_f32_e32 v178, v177
	v_pk_mul_f32 v[160:161], v[108:109], v[176:177] op_sel_hi:[1,0]
	v_pk_mul_f32 v[162:163], v[110:111], v[176:177] op_sel_hi:[1,0]
	v_pk_mul_f32 v[164:165], v[104:105], v[176:177] op_sel_hi:[1,0]
	v_pk_mul_f32 v[166:167], v[106:107], v[176:177] op_sel_hi:[1,0]
	v_exp_f32_e32 v160, v160
	v_exp_f32_e32 v161, v161
	v_exp_f32_e32 v162, v162
	v_exp_f32_e32 v163, v163
	v_exp_f32_e32 v164, v164
	v_exp_f32_e32 v165, v165
	v_exp_f32_e32 v166, v166
	v_exp_f32_e32 v167, v167
	v_pk_fma_f32 v[160:161], v[160:161], v[178:179], v[178:179] op_sel_hi:[1,0,0]
	v_pk_fma_f32 v[162:163], v[162:163], v[178:179], v[178:179] op_sel_hi:[1,0,0]
	v_pk_fma_f32 v[164:165], v[164:165], v[178:179], v[178:179] op_sel_hi:[1,0,0]
	v_pk_fma_f32 v[166:167], v[166:167], v[178:179], v[178:179] op_sel_hi:[1,0,0]
	v_rcp_f32_e32 v160, v160
	v_rcp_f32_e32 v161, v161
	v_rcp_f32_e32 v162, v162
	v_rcp_f32_e32 v163, v163
	v_rcp_f32_e32 v164, v164
	v_rcp_f32_e32 v165, v165
	v_rcp_f32_e32 v166, v166
	v_rcp_f32_e32 v167, v167
	v_pk_mul_f32 v[108:109], v[108:109], v[100:101]
	v_pk_mul_f32 v[110:111], v[110:111], v[102:103]
	v_pk_mul_f32 v[104:105], v[104:105], v[96:97]
	v_pk_mul_f32 v[106:107], v[106:107], v[98:99]
	v_pk_mul_f32 v[108:109], v[108:109], v[160:161]
	v_pk_mul_f32 v[110:111], v[110:111], v[162:163]
	v_pk_mul_f32 v[104:105], v[104:105], v[164:165]
	v_pk_mul_f32 v[106:107], v[106:107], v[166:167]
	v_cvt_pk_bf16_f32 v172, v108, v109
	v_cvt_pk_bf16_f32 v173, v110, v111
	v_cvt_pk_bf16_f32 v174, v104, v105
	v_cvt_pk_bf16_f32 v175, v106, v107
	v_add_u32_e32 v185, 0x16000, v183
	global_store_dwordx4 v185, v[172:175], s[6:7]
	v_mul_f32_e32 v176, 0xbfb8aa3b, v154
	v_mul_f32_e32 v177, v154, v154
	v_rcp_f32_e32 v178, v177
	v_pk_mul_f32 v[160:161], v[92:93], v[176:177] op_sel_hi:[1,0]
	v_pk_mul_f32 v[162:163], v[94:95], v[176:177] op_sel_hi:[1,0]
	v_pk_mul_f32 v[164:165], v[88:89], v[176:177] op_sel_hi:[1,0]
	v_pk_mul_f32 v[166:167], v[90:91], v[176:177] op_sel_hi:[1,0]
	v_exp_f32_e32 v160, v160
	v_exp_f32_e32 v161, v161
	v_exp_f32_e32 v162, v162
	v_exp_f32_e32 v163, v163
	v_exp_f32_e32 v164, v164
	v_exp_f32_e32 v165, v165
	v_exp_f32_e32 v166, v166
	v_exp_f32_e32 v167, v167
	v_pk_fma_f32 v[160:161], v[160:161], v[178:179], v[178:179] op_sel_hi:[1,0,0]
	v_pk_fma_f32 v[162:163], v[162:163], v[178:179], v[178:179] op_sel_hi:[1,0,0]
	v_pk_fma_f32 v[164:165], v[164:165], v[178:179], v[178:179] op_sel_hi:[1,0,0]
	v_pk_fma_f32 v[166:167], v[166:167], v[178:179], v[178:179] op_sel_hi:[1,0,0]
	v_rcp_f32_e32 v160, v160
	v_rcp_f32_e32 v161, v161
	v_rcp_f32_e32 v162, v162
	v_rcp_f32_e32 v163, v163
	v_rcp_f32_e32 v164, v164
	v_rcp_f32_e32 v165, v165
	v_rcp_f32_e32 v166, v166
	v_rcp_f32_e32 v167, v167
	v_pk_mul_f32 v[92:93], v[92:93], v[84:85]
	v_pk_mul_f32 v[94:95], v[94:95], v[86:87]
	v_pk_mul_f32 v[88:89], v[88:89], v[80:81]
	v_pk_mul_f32 v[90:91], v[90:91], v[82:83]
	v_pk_mul_f32 v[92:93], v[92:93], v[160:161]
	v_pk_mul_f32 v[94:95], v[94:95], v[162:163]
	v_pk_mul_f32 v[88:89], v[88:89], v[164:165]
	v_pk_mul_f32 v[90:91], v[90:91], v[166:167]
	v_cvt_pk_bf16_f32 v168, v92, v93
	v_cvt_pk_bf16_f32 v169, v94, v95
	v_cvt_pk_bf16_f32 v170, v88, v89
	v_cvt_pk_bf16_f32 v171, v90, v91
	v_add_u32_e32 v184, 0x2c000, v183
	global_store_dwordx4 v184, v[168:171], s[6:7]
	v_mul_f32_e32 v176, 0xbfb8aa3b, v155
	v_mul_f32_e32 v177, v155, v155
	v_rcp_f32_e32 v178, v177
	v_pk_mul_f32 v[160:161], v[76:77], v[176:177] op_sel_hi:[1,0]
	v_pk_mul_f32 v[162:163], v[78:79], v[176:177] op_sel_hi:[1,0]
	v_pk_mul_f32 v[164:165], v[72:73], v[176:177] op_sel_hi:[1,0]
	v_pk_mul_f32 v[166:167], v[74:75], v[176:177] op_sel_hi:[1,0]
	v_exp_f32_e32 v160, v160
	v_exp_f32_e32 v161, v161
	v_exp_f32_e32 v162, v162
	v_exp_f32_e32 v163, v163
	v_exp_f32_e32 v164, v164
	v_exp_f32_e32 v165, v165
	v_exp_f32_e32 v166, v166
	v_exp_f32_e32 v167, v167
	v_pk_fma_f32 v[160:161], v[160:161], v[178:179], v[178:179] op_sel_hi:[1,0,0]
	v_pk_fma_f32 v[162:163], v[162:163], v[178:179], v[178:179] op_sel_hi:[1,0,0]
	v_pk_fma_f32 v[164:165], v[164:165], v[178:179], v[178:179] op_sel_hi:[1,0,0]
	v_pk_fma_f32 v[166:167], v[166:167], v[178:179], v[178:179] op_sel_hi:[1,0,0]
	v_rcp_f32_e32 v160, v160
	v_rcp_f32_e32 v161, v161
	v_rcp_f32_e32 v162, v162
	v_rcp_f32_e32 v163, v163
	v_rcp_f32_e32 v164, v164
	v_rcp_f32_e32 v165, v165
	v_rcp_f32_e32 v166, v166
	v_rcp_f32_e32 v167, v167
	v_pk_mul_f32 v[76:77], v[76:77], v[68:69]
	v_pk_mul_f32 v[78:79], v[78:79], v[70:71]
	v_pk_mul_f32 v[72:73], v[72:73], v[64:65]
	v_pk_mul_f32 v[74:75], v[74:75], v[66:67]
	v_pk_mul_f32 v[76:77], v[76:77], v[160:161]
	v_pk_mul_f32 v[78:79], v[78:79], v[162:163]
	v_pk_mul_f32 v[72:73], v[72:73], v[164:165]
	v_pk_mul_f32 v[74:75], v[74:75], v[166:167]
	v_cvt_pk_bf16_f32 v172, v76, v77
	v_cvt_pk_bf16_f32 v173, v78, v79
	v_cvt_pk_bf16_f32 v174, v72, v73
	v_cvt_pk_bf16_f32 v175, v74, v75
	v_add_u32_e32 v185, 0x42000, v183
	global_store_dwordx4 v185, v[172:175], s[6:7]
	v_mul_f32_e32 v176, 0xbfb8aa3b, v156
	v_mul_f32_e32 v177, v156, v156
	v_rcp_f32_e32 v178, v177
	v_pk_mul_f32 v[160:161], v[60:61], v[176:177] op_sel_hi:[1,0]
	v_pk_mul_f32 v[162:163], v[62:63], v[176:177] op_sel_hi:[1,0]
	v_pk_mul_f32 v[164:165], v[56:57], v[176:177] op_sel_hi:[1,0]
	v_pk_mul_f32 v[166:167], v[58:59], v[176:177] op_sel_hi:[1,0]
	v_exp_f32_e32 v160, v160
	v_exp_f32_e32 v161, v161
	v_exp_f32_e32 v162, v162
	v_exp_f32_e32 v163, v163
	v_exp_f32_e32 v164, v164
	v_exp_f32_e32 v165, v165
	v_exp_f32_e32 v166, v166
	v_exp_f32_e32 v167, v167
	v_pk_fma_f32 v[160:161], v[160:161], v[178:179], v[178:179] op_sel_hi:[1,0,0]
	v_pk_fma_f32 v[162:163], v[162:163], v[178:179], v[178:179] op_sel_hi:[1,0,0]
	v_pk_fma_f32 v[164:165], v[164:165], v[178:179], v[178:179] op_sel_hi:[1,0,0]
	v_pk_fma_f32 v[166:167], v[166:167], v[178:179], v[178:179] op_sel_hi:[1,0,0]
	v_rcp_f32_e32 v160, v160
	v_rcp_f32_e32 v161, v161
	v_rcp_f32_e32 v162, v162
	v_rcp_f32_e32 v163, v163
	v_rcp_f32_e32 v164, v164
	v_rcp_f32_e32 v165, v165
	v_rcp_f32_e32 v166, v166
	v_rcp_f32_e32 v167, v167
	v_pk_mul_f32 v[60:61], v[60:61], v[52:53]
	v_pk_mul_f32 v[62:63], v[62:63], v[54:55]
	v_pk_mul_f32 v[56:57], v[56:57], v[48:49]
	v_pk_mul_f32 v[58:59], v[58:59], v[50:51]
	v_pk_mul_f32 v[60:61], v[60:61], v[160:161]
	v_pk_mul_f32 v[62:63], v[62:63], v[162:163]
	v_pk_mul_f32 v[56:57], v[56:57], v[164:165]
	v_pk_mul_f32 v[58:59], v[58:59], v[166:167]
	v_cvt_pk_bf16_f32 v168, v60, v61
	v_cvt_pk_bf16_f32 v169, v62, v63
	v_cvt_pk_bf16_f32 v170, v56, v57
	v_cvt_pk_bf16_f32 v171, v58, v59
	v_add_u32_e32 v184, 0xb0000, v183
	global_store_dwordx4 v184, v[168:171], s[6:7]
	v_mul_f32_e32 v176, 0xbfb8aa3b, v157
	v_mul_f32_e32 v177, v157, v157
	v_rcp_f32_e32 v178, v177
	v_pk_mul_f32 v[160:161], v[44:45], v[176:177] op_sel_hi:[1,0]
	v_pk_mul_f32 v[162:163], v[46:47], v[176:177] op_sel_hi:[1,0]
	v_pk_mul_f32 v[164:165], v[40:41], v[176:177] op_sel_hi:[1,0]
	v_pk_mul_f32 v[166:167], v[42:43], v[176:177] op_sel_hi:[1,0]
	v_exp_f32_e32 v160, v160
	v_exp_f32_e32 v161, v161
	v_exp_f32_e32 v162, v162
	v_exp_f32_e32 v163, v163
	v_exp_f32_e32 v164, v164
	v_exp_f32_e32 v165, v165
	v_exp_f32_e32 v166, v166
	v_exp_f32_e32 v167, v167
	v_pk_fma_f32 v[160:161], v[160:161], v[178:179], v[178:179] op_sel_hi:[1,0,0]
	v_pk_fma_f32 v[162:163], v[162:163], v[178:179], v[178:179] op_sel_hi:[1,0,0]
	v_pk_fma_f32 v[164:165], v[164:165], v[178:179], v[178:179] op_sel_hi:[1,0,0]
	v_pk_fma_f32 v[166:167], v[166:167], v[178:179], v[178:179] op_sel_hi:[1,0,0]
	v_rcp_f32_e32 v160, v160
	v_rcp_f32_e32 v161, v161
	v_rcp_f32_e32 v162, v162
	v_rcp_f32_e32 v163, v163
	v_rcp_f32_e32 v164, v164
	v_rcp_f32_e32 v165, v165
	v_rcp_f32_e32 v166, v166
	v_rcp_f32_e32 v167, v167
	v_pk_mul_f32 v[44:45], v[44:45], v[36:37]
	v_pk_mul_f32 v[46:47], v[46:47], v[38:39]
	v_pk_mul_f32 v[40:41], v[40:41], v[32:33]
	v_pk_mul_f32 v[42:43], v[42:43], v[34:35]
	v_pk_mul_f32 v[44:45], v[44:45], v[160:161]
	v_pk_mul_f32 v[46:47], v[46:47], v[162:163]
	v_pk_mul_f32 v[40:41], v[40:41], v[164:165]
	v_pk_mul_f32 v[42:43], v[42:43], v[166:167]
	v_cvt_pk_bf16_f32 v172, v44, v45
	v_cvt_pk_bf16_f32 v173, v46, v47
	v_cvt_pk_bf16_f32 v174, v40, v41
	v_cvt_pk_bf16_f32 v175, v42, v43
	v_add_u32_e32 v185, 0xc6000, v183
	global_store_dwordx4 v185, v[172:175], s[6:7]
	v_mul_f32_e32 v176, 0xbfb8aa3b, v158
	v_mul_f32_e32 v177, v158, v158
	v_rcp_f32_e32 v178, v177
	v_pk_mul_f32 v[160:161], v[28:29], v[176:177] op_sel_hi:[1,0]
	v_pk_mul_f32 v[162:163], v[30:31], v[176:177] op_sel_hi:[1,0]
	v_pk_mul_f32 v[164:165], v[24:25], v[176:177] op_sel_hi:[1,0]
	v_pk_mul_f32 v[166:167], v[26:27], v[176:177] op_sel_hi:[1,0]
	v_exp_f32_e32 v160, v160
	v_exp_f32_e32 v161, v161
	v_exp_f32_e32 v162, v162
	v_exp_f32_e32 v163, v163
	v_exp_f32_e32 v164, v164
	v_exp_f32_e32 v165, v165
	v_exp_f32_e32 v166, v166
	v_exp_f32_e32 v167, v167
	v_pk_fma_f32 v[160:161], v[160:161], v[178:179], v[178:179] op_sel_hi:[1,0,0]
	v_pk_fma_f32 v[162:163], v[162:163], v[178:179], v[178:179] op_sel_hi:[1,0,0]
	v_pk_fma_f32 v[164:165], v[164:165], v[178:179], v[178:179] op_sel_hi:[1,0,0]
	v_pk_fma_f32 v[166:167], v[166:167], v[178:179], v[178:179] op_sel_hi:[1,0,0]
	v_rcp_f32_e32 v160, v160
	v_rcp_f32_e32 v161, v161
	v_rcp_f32_e32 v162, v162
	v_rcp_f32_e32 v163, v163
	v_rcp_f32_e32 v164, v164
	v_rcp_f32_e32 v165, v165
	v_rcp_f32_e32 v166, v166
	v_rcp_f32_e32 v167, v167
	v_pk_mul_f32 v[28:29], v[28:29], v[20:21]
	v_pk_mul_f32 v[30:31], v[30:31], v[22:23]
	v_pk_mul_f32 v[24:25], v[24:25], v[16:17]
	v_pk_mul_f32 v[26:27], v[26:27], v[18:19]
	v_pk_mul_f32 v[28:29], v[28:29], v[160:161]
	v_pk_mul_f32 v[30:31], v[30:31], v[162:163]
	v_pk_mul_f32 v[24:25], v[24:25], v[164:165]
	v_pk_mul_f32 v[26:27], v[26:27], v[166:167]
	v_cvt_pk_bf16_f32 v168, v28, v29
	v_cvt_pk_bf16_f32 v169, v30, v31
	v_cvt_pk_bf16_f32 v170, v24, v25
	v_cvt_pk_bf16_f32 v171, v26, v27
	v_add_u32_e32 v184, 0xdc000, v183
	global_store_dwordx4 v184, v[168:171], s[6:7]
	v_mul_f32_e32 v176, 0xbfb8aa3b, v159
	v_mul_f32_e32 v177, v159, v159
	v_rcp_f32_e32 v178, v177
	v_pk_mul_f32 v[160:161], v[12:13], v[176:177] op_sel_hi:[1,0]
	v_pk_mul_f32 v[162:163], v[14:15], v[176:177] op_sel_hi:[1,0]
	v_pk_mul_f32 v[164:165], v[8:9], v[176:177] op_sel_hi:[1,0]
	v_pk_mul_f32 v[166:167], v[10:11], v[176:177] op_sel_hi:[1,0]
	v_exp_f32_e32 v160, v160
	v_exp_f32_e32 v161, v161
	v_exp_f32_e32 v162, v162
	v_exp_f32_e32 v163, v163
	v_exp_f32_e32 v164, v164
	v_exp_f32_e32 v165, v165
	v_exp_f32_e32 v166, v166
	v_exp_f32_e32 v167, v167
	v_pk_fma_f32 v[160:161], v[160:161], v[178:179], v[178:179] op_sel_hi:[1,0,0]
	v_pk_fma_f32 v[162:163], v[162:163], v[178:179], v[178:179] op_sel_hi:[1,0,0]
	v_pk_fma_f32 v[164:165], v[164:165], v[178:179], v[178:179] op_sel_hi:[1,0,0]
	v_pk_fma_f32 v[166:167], v[166:167], v[178:179], v[178:179] op_sel_hi:[1,0,0]
	v_rcp_f32_e32 v160, v160
	v_rcp_f32_e32 v161, v161
	v_rcp_f32_e32 v162, v162
	v_rcp_f32_e32 v163, v163
	v_rcp_f32_e32 v164, v164
	v_rcp_f32_e32 v165, v165
	v_rcp_f32_e32 v166, v166
	v_rcp_f32_e32 v167, v167
	v_pk_mul_f32 v[12:13], v[12:13], v[4:5]
	v_pk_mul_f32 v[14:15], v[14:15], v[6:7]
	v_pk_mul_f32 v[8:9], v[8:9], v[0:1]
	v_pk_mul_f32 v[10:11], v[10:11], v[2:3]
	v_pk_mul_f32 v[12:13], v[12:13], v[160:161]
	v_pk_mul_f32 v[14:15], v[14:15], v[162:163]
	v_pk_mul_f32 v[8:9], v[8:9], v[164:165]
	v_pk_mul_f32 v[10:11], v[10:11], v[166:167]
	v_cvt_pk_bf16_f32 v172, v12, v13
	v_cvt_pk_bf16_f32 v173, v14, v15
	v_cvt_pk_bf16_f32 v174, v8, v9
	v_cvt_pk_bf16_f32 v175, v10, v11
	v_add_u32_e32 v185, 0xf2000, v183
	global_store_dwordx4 v185, v[172:175], s[6:7]
	s_cbranch_vccz .LBB0_890
	s_waitcnt vmcnt(0)
	s_cmpk_gt_u32 s30, 0xff
	s_cbranch_scc1 .LBB0_897
